# mem_tile: 8 key steps unrolled over a 3-buffer K/V rotation (K,V one step ahead), q loads issued together
# speedup vs baseline: 1.0035x; 1.0035x over previous
; __device__ __forceinline__ bf16x8 scale_q(u32x4 v, float s) { u32x4 w; w.x = cvt_pk_bf16(bf_lo(v.x) * s, bf_hi(v.x) * s); w.y = cvt_pk_bf16(bf_lo(v.y) * s, bf_hi(v.y) * s); w.z = cvt_pk_bf16(bf_lo(v.z) * s, bf_hi(v.z) * s); w.w = cvt_pk_bf16(bf_lo(v.w) * s, bf_hi(v.w) * s); return __builtin_bit_cast(bf16x8, w); }
; __device__ __forceinline__ void mem_tile(const Ctx& C, int b, int hm, int t0) {
;     ...
;     const float QS = 0.12751743082459868f;
;     bf16x8 q[8];
;     const bf16_t* qp = P + tok * PP + PC_QM + hm * 128;
; #pragma unroll
;     for (int s = 0; s < 8; ++s) q[s] = scale_q(*(const u32x4*)(qp + 16 * s + 8 * hi), QS);
;     const bf16x8* kb = (const bf16x8*)(C.ws + WS_MEMK) + (size_t)(b * 4 + hm) * 8 * 8 * 64 + lane;
;     const bf16x8* vb = (const bf16x8*)(C.ws + WS_MEMV) + (size_t)(b * 4 + hm) * 16 * 4 * 64 + lane;
;     float m = -1e30f, l = 0.f; f32x16 O[4];
; #pragma unroll
;     for (int i = 0; i < 16; ++i) { O[0][i] = 0.f; O[1][i] = 0.f; O[2][i] = 0.f; O[3][i] = 0.f; }
;     ...
;     {
;         bf16x8 kA[8], vv[8];
; #pragma unroll 1
;         for (int kt = 0; kt < 8; ++kt) {
; #pragma unroll
;             for (int s = 0; s < 8; ++s) kA[s] = kb[kt * 512 + s * 64];
; #pragma unroll
;             for (int s = 0; s < 8; ++s) vv[s] = vb[kt * 512 + s * 64];
.LBB0_657:
	s_ashr_i32 s0, s5, 11
	s_lshl_b32 s1, s5, 5
	s_and_b32 s3, s1, 0x3fe0
	s_ashr_i32 s1, s0, 31
	s_lshl_b64 s[10:11], s[0:1], 14
	v_mov_b32_e32 v6, v252
	s_or_b32 s1, s10, s3
	v_mov_b64_e32 v[2:3], s[34:35]
	s_waitcnt vmcnt(12)
	v_and_or_b32 v146, v6, 31, s1
	s_bfe_u32 s4, s5, 0x20009
	v_ashrrev_i32_e32 v152, 5, v6
	v_mad_u64_u32 v[148:149], s[12:13], v146, s67, v[2:3]
	v_mad_i32_i24 v149, s11, v233, v149
	s_lshl_b32 s6, s4, 8
	v_lshlrev_b32_e32 v4, 3, v152
	v_lshl_add_u64 v[2:3], v[148:149], 0, s[6:7]
	v_ashrrev_i32_e32 v5, 31, v4
	v_mov_b32_e32 v147, s11
	v_lshl_add_u64 v[4:5], v[4:5], 1, v[2:3]
	s_mov_b64 s[10:11], 0x10201600
	s_mov_b32 s1, 0x10201000
	v_lshl_add_u64 v[2:3], v[4:5], 0, s[10:11]
	v_add_co_u32_e32 v4, vcc, s1, v4
	s_lshl_b32 s0, s0, 2
	s_nop 0
	v_addc_co_u32_e32 v5, vcc, 0, v5, vcc
	global_load_dwordx4 v[8:11], v[4:5], off offset:1536
	global_load_dwordx4 v[16:19], v[2:3], off offset:32
	global_load_dwordx4 v[20:23], v[2:3], off offset:64
	global_load_dwordx4 v[24:27], v[2:3], off offset:96
	global_load_dwordx4 v[28:31], v[2:3], off offset:128
	global_load_dwordx4 v[32:35], v[2:3], off offset:160
	global_load_dwordx4 v[36:39], v[2:3], off offset:192
	global_load_dwordx4 v[40:43], v[2:3], off offset:224
	s_or_b32 s0, s0, s4
	s_ashr_i32 s1, s0, 31
	s_lshl_b32 s3, s4, 7
	s_lshl_b64 s[0:1], s[0:1], 16
	s_add_u32 s0, s34, s0
	v_ashrrev_i32_e32 v7, 31, v6
	s_addc_u32 s1, s35, s1
	v_mov_b32_e32 v14, v1
	v_mov_b32_e32 v15, v1
	v_lshl_add_u64 v[150:151], v[6:7], 4, s[0:1]
	s_mov_b64 s[10:11], 0x3c00000
	v_lshl_add_u64 v[224:225], v[150:151], 0, s[10:11]
	s_mov_b32 s10, 0x3c01000
	v_lshl_add_u64 v[226:227], v[150:151], 0, s[10:11]
	s_mov_b32 s10, 0x3c80000
	v_lshl_add_u64 v[228:229], v[150:151], 0, s[10:11]
	s_mov_b32 s10, 0x3c81000
	v_lshl_add_u64 v[230:231], v[150:151], 0, s[10:11]
	s_mov_b64 s[12:13], 0x2000
	global_load_dwordx4 v[184:187], v[224:225], off
	global_load_dwordx4 v[156:159], v[224:225], off offset:1024
	global_load_dwordx4 v[160:163], v[224:225], off offset:2048
	global_load_dwordx4 v[164:167], v[224:225], off offset:3072
	global_load_dwordx4 v[168:171], v[226:227], off
	global_load_dwordx4 v[172:175], v[226:227], off offset:1024
	global_load_dwordx4 v[176:179], v[226:227], off offset:2048
	global_load_dwordx4 v[180:183], v[226:227], off offset:3072
	v_lshl_add_u64 v[224:225], v[224:225], 0, s[12:13]
	v_lshl_add_u64 v[226:227], v[226:227], 0, s[12:13]
	global_load_dwordx4 v[114:117], v[228:229], off
	global_load_dwordx4 v[118:121], v[228:229], off offset:1024
	global_load_dwordx4 v[122:125], v[228:229], off offset:2048
	global_load_dwordx4 v[126:129], v[228:229], off offset:3072
	global_load_dwordx4 v[130:133], v[230:231], off
	global_load_dwordx4 v[134:137], v[230:231], off offset:1024
	global_load_dwordx4 v[138:141], v[230:231], off offset:2048
	global_load_dwordx4 v[142:145], v[230:231], off offset:3072
	v_lshl_add_u64 v[228:229], v[228:229], 0, s[12:13]
	v_lshl_add_u64 v[230:231], v[230:231], 0, s[12:13]
	global_load_dwordx4 v[188:191], v[224:225], off
	global_load_dwordx4 v[192:195], v[224:225], off offset:1024
	global_load_dwordx4 v[196:199], v[224:225], off offset:2048
	global_load_dwordx4 v[200:203], v[224:225], off offset:3072
	global_load_dwordx4 v[204:207], v[226:227], off
	global_load_dwordx4 v[208:211], v[226:227], off offset:1024
	global_load_dwordx4 v[216:219], v[226:227], off offset:2048
	global_load_dwordx4 v[220:223], v[226:227], off offset:3072
	v_lshl_add_u64 v[224:225], v[224:225], 0, s[12:13]
	v_lshl_add_u64 v[226:227], v[226:227], 0, s[12:13]
	v_mov_b32_e32 v0, v1
	v_mov_b32_e32 v6, v1
	v_mov_b32_e32 v7, v1
	v_mov_b32_e32 v12, v1
	v_mov_b32_e32 v13, v1
	v_mov_b32_e32 v153, 0
	v_mov_b32_e32 v154, 0xf149f2ca
	s_waitcnt vmcnt(24)
	v_lshlrev_b32_e32 v4, 16, v8
	v_and_b32_e32 v5, 0xffff0000, v8
	v_pk_mul_f32 v[4:5], v[4:5], s[14:15] op_sel_hi:[1,0]
	s_nop 0
	v_cvt_pk_bf16_f32 v82, v4, v5
	v_lshlrev_b32_e32 v4, 16, v9
	v_and_b32_e32 v5, 0xffff0000, v9
	v_pk_mul_f32 v[4:5], v[4:5], s[14:15] op_sel_hi:[1,0]
	s_nop 0
	v_cvt_pk_bf16_f32 v83, v4, v5
	v_lshlrev_b32_e32 v4, 16, v10
	v_and_b32_e32 v5, 0xffff0000, v10
	v_pk_mul_f32 v[4:5], v[4:5], s[14:15] op_sel_hi:[1,0]
	s_nop 0
	v_cvt_pk_bf16_f32 v84, v4, v5
	v_lshlrev_b32_e32 v4, 16, v11
	v_and_b32_e32 v5, 0xffff0000, v11
	v_mov_b32_e32 v8, v16
	v_mov_b32_e32 v9, v17
	v_mov_b32_e32 v10, v18
	v_mov_b32_e32 v11, v19
	v_pk_mul_f32 v[4:5], v[4:5], s[14:15] op_sel_hi:[1,0]
	s_nop 0
	v_cvt_pk_bf16_f32 v85, v4, v5
	s_waitcnt vmcnt(24)
	v_lshlrev_b32_e32 v4, 16, v8
	v_and_b32_e32 v5, 0xffff0000, v8
	v_pk_mul_f32 v[4:5], v[4:5], s[14:15] op_sel_hi:[1,0]
	s_nop 0
	v_cvt_pk_bf16_f32 v86, v4, v5
	v_lshlrev_b32_e32 v4, 16, v9
	v_and_b32_e32 v5, 0xffff0000, v9
	v_pk_mul_f32 v[4:5], v[4:5], s[14:15] op_sel_hi:[1,0]
	s_nop 0
	v_cvt_pk_bf16_f32 v87, v4, v5
	v_lshlrev_b32_e32 v4, 16, v10
	v_and_b32_e32 v5, 0xffff0000, v10
	v_pk_mul_f32 v[4:5], v[4:5], s[14:15] op_sel_hi:[1,0]
	s_nop 0
	v_cvt_pk_bf16_f32 v88, v4, v5
	v_lshlrev_b32_e32 v4, 16, v11
	v_and_b32_e32 v5, 0xffff0000, v11
	v_mov_b32_e32 v8, v20
	v_mov_b32_e32 v9, v21
	v_mov_b32_e32 v10, v22
	v_mov_b32_e32 v11, v23
	v_pk_mul_f32 v[4:5], v[4:5], s[14:15] op_sel_hi:[1,0]
	s_nop 0
	v_cvt_pk_bf16_f32 v89, v4, v5
	s_waitcnt vmcnt(24)
	v_lshlrev_b32_e32 v4, 16, v8
	v_and_b32_e32 v5, 0xffff0000, v8
	v_pk_mul_f32 v[4:5], v[4:5], s[14:15] op_sel_hi:[1,0]
	s_nop 0
	v_cvt_pk_bf16_f32 v90, v4, v5
	v_lshlrev_b32_e32 v4, 16, v9
	v_and_b32_e32 v5, 0xffff0000, v9
	v_pk_mul_f32 v[4:5], v[4:5], s[14:15] op_sel_hi:[1,0]
	s_nop 0
	v_cvt_pk_bf16_f32 v91, v4, v5
	v_lshlrev_b32_e32 v4, 16, v10
	v_and_b32_e32 v5, 0xffff0000, v10
	v_pk_mul_f32 v[4:5], v[4:5], s[14:15] op_sel_hi:[1,0]
	s_nop 0
	v_cvt_pk_bf16_f32 v92, v4, v5
	v_lshlrev_b32_e32 v4, 16, v11
	v_and_b32_e32 v5, 0xffff0000, v11
	v_mov_b32_e32 v8, v24
	v_mov_b32_e32 v9, v25
	v_mov_b32_e32 v10, v26
	v_mov_b32_e32 v11, v27
	v_pk_mul_f32 v[4:5], v[4:5], s[14:15] op_sel_hi:[1,0]
	s_nop 0
	v_cvt_pk_bf16_f32 v93, v4, v5
	s_waitcnt vmcnt(24)
; __device__ __forceinline__ bf16x8 scale_q(u32x4 v, float s) { u32x4 w; w.x = cvt_pk_bf16(bf_lo(v.x) * s, bf_hi(v.x) * s); w.y = cvt_pk_bf16(bf_lo(v.y) * s, bf_hi(v.y) * s); w.z = cvt_pk_bf16(bf_lo(v.z) * s, bf_hi(v.z) * s); w.w = cvt_pk_bf16(bf_lo(v.w) * s, bf_hi(v.w) * s); return __builtin_bit_cast(bf16x8, w); }
; __device__ __forceinline__ void mem_tile(const Ctx& C, int b, int hm, int t0) {
;     ...
;     bf16x8 q[8];
;     const bf16_t* qp = P + tok * PP + PC_QM + hm * 128;
; #pragma unroll
;     for (int s = 0; s < 8; ++s) q[s] = scale_q(*(const u32x4*)(qp + 16 * s + 8 * hi), QS);
;     const bf16x8* kb = (const bf16x8*)(C.ws + WS_MEMK) + (size_t)(b * 4 + hm) * 8 * 8 * 64 + lane;
;     const bf16x8* vb = (const bf16x8*)(C.ws + WS_MEMV) + (size_t)(b * 4 + hm) * 16 * 4 * 64 + lane;
;     float m = -1e30f, l = 0.f; f32x16 O[4];
; #pragma unroll
;     for (int i = 0; i < 16; ++i) { O[0][i] = 0.f; O[1][i] = 0.f; O[2][i] = 0.f; O[3][i] = 0.f; }
	v_lshlrev_b32_e32 v4, 16, v8
	v_and_b32_e32 v5, 0xffff0000, v8
	v_pk_mul_f32 v[4:5], v[4:5], s[14:15] op_sel_hi:[1,0]
	s_nop 0
	v_cvt_pk_bf16_f32 v94, v4, v5
	v_lshlrev_b32_e32 v4, 16, v9
	v_and_b32_e32 v5, 0xffff0000, v9
	v_pk_mul_f32 v[4:5], v[4:5], s[14:15] op_sel_hi:[1,0]
	s_nop 0
	v_cvt_pk_bf16_f32 v95, v4, v5
	v_lshlrev_b32_e32 v4, 16, v10
	v_and_b32_e32 v5, 0xffff0000, v10
	v_pk_mul_f32 v[4:5], v[4:5], s[14:15] op_sel_hi:[1,0]
	s_nop 0
	v_cvt_pk_bf16_f32 v96, v4, v5
	v_lshlrev_b32_e32 v4, 16, v11
	v_and_b32_e32 v5, 0xffff0000, v11
	v_mov_b32_e32 v8, v28
	v_mov_b32_e32 v9, v29
	v_mov_b32_e32 v10, v30
	v_mov_b32_e32 v11, v31
	v_pk_mul_f32 v[4:5], v[4:5], s[14:15] op_sel_hi:[1,0]
	s_nop 0
	v_cvt_pk_bf16_f32 v97, v4, v5
	s_waitcnt vmcnt(24)
	v_lshlrev_b32_e32 v4, 16, v8
	v_and_b32_e32 v5, 0xffff0000, v8
	v_pk_mul_f32 v[4:5], v[4:5], s[14:15] op_sel_hi:[1,0]
	s_nop 0
	v_cvt_pk_bf16_f32 v98, v4, v5
	v_lshlrev_b32_e32 v4, 16, v9
	v_and_b32_e32 v5, 0xffff0000, v9
	v_pk_mul_f32 v[4:5], v[4:5], s[14:15] op_sel_hi:[1,0]
	s_nop 0
	v_cvt_pk_bf16_f32 v99, v4, v5
	v_lshlrev_b32_e32 v4, 16, v10
	v_and_b32_e32 v5, 0xffff0000, v10
	v_pk_mul_f32 v[4:5], v[4:5], s[14:15] op_sel_hi:[1,0]
	s_nop 0
	v_cvt_pk_bf16_f32 v100, v4, v5
	v_lshlrev_b32_e32 v4, 16, v11
	v_and_b32_e32 v5, 0xffff0000, v11
	v_mov_b32_e32 v8, v32
	v_mov_b32_e32 v9, v33
	v_mov_b32_e32 v10, v34
	v_mov_b32_e32 v11, v35
	v_pk_mul_f32 v[4:5], v[4:5], s[14:15] op_sel_hi:[1,0]
	s_nop 0
	v_cvt_pk_bf16_f32 v101, v4, v5
	s_waitcnt vmcnt(24)
	v_lshlrev_b32_e32 v4, 16, v8
	v_and_b32_e32 v5, 0xffff0000, v8
	v_pk_mul_f32 v[4:5], v[4:5], s[14:15] op_sel_hi:[1,0]
	s_nop 0
	v_cvt_pk_bf16_f32 v102, v4, v5
	v_lshlrev_b32_e32 v4, 16, v9
	v_and_b32_e32 v5, 0xffff0000, v9
	v_pk_mul_f32 v[4:5], v[4:5], s[14:15] op_sel_hi:[1,0]
	s_nop 0
	v_cvt_pk_bf16_f32 v103, v4, v5
	v_lshlrev_b32_e32 v4, 16, v10
	v_and_b32_e32 v5, 0xffff0000, v10
	v_pk_mul_f32 v[4:5], v[4:5], s[14:15] op_sel_hi:[1,0]
	s_nop 0
	v_cvt_pk_bf16_f32 v104, v4, v5
	v_lshlrev_b32_e32 v4, 16, v11
	v_and_b32_e32 v5, 0xffff0000, v11
	v_mov_b32_e32 v8, v36
	v_mov_b32_e32 v9, v37
	v_mov_b32_e32 v10, v38
	v_mov_b32_e32 v11, v39
	v_pk_mul_f32 v[4:5], v[4:5], s[14:15] op_sel_hi:[1,0]
	s_nop 0
	v_cvt_pk_bf16_f32 v105, v4, v5
	s_waitcnt vmcnt(24)
	v_lshlrev_b32_e32 v4, 16, v8
	v_and_b32_e32 v5, 0xffff0000, v8
	v_pk_mul_f32 v[4:5], v[4:5], s[14:15] op_sel_hi:[1,0]
	s_nop 0
	v_cvt_pk_bf16_f32 v106, v4, v5
	v_lshlrev_b32_e32 v4, 16, v9
	v_and_b32_e32 v5, 0xffff0000, v9
	v_pk_mul_f32 v[4:5], v[4:5], s[14:15] op_sel_hi:[1,0]
	s_nop 0
	v_cvt_pk_bf16_f32 v107, v4, v5
	v_lshlrev_b32_e32 v4, 16, v10
	v_and_b32_e32 v5, 0xffff0000, v10
	v_pk_mul_f32 v[4:5], v[4:5], s[14:15] op_sel_hi:[1,0]
	v_mov_b32_e32 v10, v1
	v_cvt_pk_bf16_f32 v108, v4, v5
	v_lshlrev_b32_e32 v4, 16, v11
	v_and_b32_e32 v5, 0xffff0000, v11
	v_pk_mul_f32 v[4:5], v[4:5], s[14:15] op_sel_hi:[1,0]
	v_mov_b32_e32 v11, v1
	v_cvt_pk_bf16_f32 v109, v4, v5
	v_mov_b32_e32 v2, v40
	v_mov_b32_e32 v3, v41
	v_mov_b32_e32 v4, v42
	v_mov_b32_e32 v5, v43
	s_waitcnt vmcnt(24)
	v_lshlrev_b32_e32 v8, 16, v2
	v_and_b32_e32 v9, 0xffff0000, v2
	v_lshlrev_b32_e32 v2, 16, v3
	v_and_b32_e32 v3, 0xffff0000, v3
	v_pk_mul_f32 v[2:3], v[2:3], s[14:15] op_sel_hi:[1,0]
	v_pk_mul_f32 v[8:9], v[8:9], s[14:15] op_sel_hi:[1,0]
	v_cvt_pk_bf16_f32 v111, v2, v3
	v_lshlrev_b32_e32 v2, 16, v4
	v_and_b32_e32 v3, 0xffff0000, v4
	v_pk_mul_f32 v[2:3], v[2:3], s[14:15] op_sel_hi:[1,0]
	v_cvt_pk_bf16_f32 v110, v8, v9
	v_cvt_pk_bf16_f32 v112, v2, v3
	v_lshlrev_b32_e32 v2, 16, v5
	v_and_b32_e32 v3, 0xffff0000, v5
	v_pk_mul_f32 v[2:3], v[2:3], s[14:15] op_sel_hi:[1,0]
	v_mov_b32_e32 v4, v1
	v_cvt_pk_bf16_f32 v113, v2, v3
	v_mov_b32_e32 v2, v1
	v_mov_b32_e32 v3, v1
	v_mov_b32_e32 v5, v1
	v_mov_b32_e32 v8, v1
	v_mov_b32_e32 v9, v1
	v_mov_b64_e32 v[64:65], v[14:15]
	v_mov_b64_e32 v[48:49], v[14:15]
	v_mov_b64_e32 v[32:33], v[14:15]
	v_mov_b64_e32 v[62:63], v[12:13]
	v_mov_b64_e32 v[60:61], v[10:11]
	v_mov_b64_e32 v[58:59], v[8:9]
	v_mov_b64_e32 v[56:57], v[6:7]
	v_mov_b64_e32 v[54:55], v[4:5]
	v_mov_b64_e32 v[52:53], v[2:3]
	v_mov_b64_e32 v[50:51], v[0:1]
	v_mov_b64_e32 v[46:47], v[12:13]
	v_mov_b64_e32 v[44:45], v[10:11]
	v_mov_b64_e32 v[42:43], v[8:9]
	v_mov_b64_e32 v[40:41], v[6:7]
	v_mov_b64_e32 v[38:39], v[4:5]
	v_mov_b64_e32 v[36:37], v[2:3]
	v_mov_b64_e32 v[34:35], v[0:1]
	v_mov_b64_e32 v[30:31], v[12:13]
	v_mov_b64_e32 v[28:29], v[10:11]
	v_mov_b64_e32 v[26:27], v[8:9]
	v_mov_b64_e32 v[24:25], v[6:7]
	v_mov_b64_e32 v[22:23], v[4:5]
	v_mov_b64_e32 v[20:21], v[2:3]
	v_mov_b64_e32 v[18:19], v[0:1]
	v_mov_b64_e32 v[16:17], v[14:15]
	v_mov_b64_e32 v[14:15], v[12:13]
	v_mov_b64_e32 v[12:13], v[10:11]
	v_mov_b64_e32 v[10:11], v[8:9]
	v_mov_b64_e32 v[8:9], v[6:7]
	v_mov_b64_e32 v[6:7], v[4:5]
	v_mov_b64_e32 v[4:5], v[2:3]
	v_mov_b64_e32 v[2:3], v[0:1]
	s_waitcnt vmcnt(23)
	v_mfma_f32_32x32x16_bf16 v[66:81], v[184:187], v[82:85], 0
	s_waitcnt vmcnt(22)
	v_mfma_f32_32x32x16_bf16 v[66:81], v[156:159], v[86:89], v[66:81]
	s_waitcnt vmcnt(21)
	v_mfma_f32_32x32x16_bf16 v[66:81], v[160:163], v[90:93], v[66:81]
	s_waitcnt vmcnt(20)
	v_mfma_f32_32x32x16_bf16 v[66:81], v[164:167], v[94:97], v[66:81]
	s_waitcnt vmcnt(19)
	v_mfma_f32_32x32x16_bf16 v[66:81], v[168:171], v[98:101], v[66:81]
	s_waitcnt vmcnt(18)
	v_mfma_f32_32x32x16_bf16 v[66:81], v[172:175], v[102:105], v[66:81]
	s_waitcnt vmcnt(17)
	v_mfma_f32_32x32x16_bf16 v[66:81], v[176:179], v[106:109], v[66:81]
	s_waitcnt vmcnt(16)
	v_mfma_f32_32x32x16_bf16 v[66:81], v[180:183], v[110:113], v[66:81]
	global_load_dwordx4 v[184:187], v[228:229], off
	global_load_dwordx4 v[156:159], v[228:229], off offset:1024
	global_load_dwordx4 v[160:163], v[228:229], off offset:2048
	global_load_dwordx4 v[164:167], v[228:229], off offset:3072
	global_load_dwordx4 v[168:171], v[230:231], off
	global_load_dwordx4 v[172:175], v[230:231], off offset:1024
	global_load_dwordx4 v[176:179], v[230:231], off offset:2048
	global_load_dwordx4 v[180:183], v[230:231], off offset:3072
	v_lshl_add_u64 v[228:229], v[228:229], 0, s[12:13]
	v_lshl_add_u64 v[230:231], v[230:231], 0, s[12:13]
	s_nop 11
	v_max3_f32 v0, v66, s56, v67
	v_max3_f32 v0, v0, v68, v69
	v_max3_f32 v0, v0, v70, v71
	v_max3_f32 v0, v0, v72, v73
	v_max3_f32 v0, v0, v74, v75
	v_max3_f32 v0, v0, v76, v77
	v_max3_f32 v0, v0, v78, v79
	v_max3_f32 v0, v0, v80, v81
	v_mov_b32_e32 v155, v0
	s_nop 1
	v_permlane32_swap_b32_e32 v0, v155
	v_max_f32_e32 v155, v155, v155
	v_max_f32_e32 v0, v0, v0
	v_max_f32_e32 v0, v0, v155
	v_add_f32_e32 v155, 0x41000000, v154
	v_cmp_gt_f32_e32 vcc, v0, v155
	s_cbranch_vccnz .Lmem_upd_0
.Lmem_cont_0:
	v_sub_f32_e32 v0, v66, v154
	v_exp_f32_e32 v0, v0
	v_sub_f32_e32 v67, v67, v154
	v_exp_f32_e32 v67, v67
	v_sub_f32_e32 v68, v68, v154
	v_exp_f32_e32 v68, v68
	v_sub_f32_e32 v69, v69, v154
	v_exp_f32_e32 v69, v69
	v_sub_f32_e32 v70, v70, v154
	v_add_f32_e32 v66, 0, v0
	v_exp_f32_e32 v70, v70
	v_sub_f32_e32 v71, v71, v154
	v_add_f32_e32 v66, v67, v66
	v_exp_f32_e32 v71, v71
	v_sub_f32_e32 v72, v72, v154
	v_add_f32_e32 v66, v68, v66
	v_exp_f32_e32 v72, v72
	v_sub_f32_e32 v73, v73, v154
	v_add_f32_e32 v66, v69, v66
	v_exp_f32_e32 v73, v73
	v_sub_f32_e32 v74, v74, v154
	v_add_f32_e32 v66, v70, v66
	v_exp_f32_e32 v74, v74
	v_sub_f32_e32 v75, v75, v154
	v_add_f32_e32 v66, v71, v66
	v_exp_f32_e32 v75, v75
	v_sub_f32_e32 v76, v76, v154
	v_add_f32_e32 v66, v72, v66
	v_exp_f32_e32 v76, v76
	v_sub_f32_e32 v77, v77, v154
	v_add_f32_e32 v66, v73, v66
	v_exp_f32_e32 v77, v77
	v_sub_f32_e32 v78, v78, v154
	v_add_f32_e32 v66, v74, v66
	v_exp_f32_e32 v78, v78
	v_sub_f32_e32 v79, v79, v154
	v_add_f32_e32 v66, v75, v66
	v_exp_f32_e32 v79, v79
	v_sub_f32_e32 v80, v80, v154
	v_add_f32_e32 v66, v76, v66
	v_exp_f32_e32 v80, v80
	v_sub_f32_e32 v81, v81, v154
	v_add_f32_e32 v66, v77, v66
	v_exp_f32_e32 v81, v81
	v_add_f32_e32 v66, v78, v66
	v_add_f32_e32 v66, v79, v66
	v_add_f32_e32 v66, v80, v66
	v_add_f32_e32 v155, v81, v66
	v_cvt_pk_bf16_f32 v66, v0, v67
	v_cvt_pk_bf16_f32 v67, v68, v69
	v_cvt_pk_bf16_f32 v68, v70, v71
	v_cvt_pk_bf16_f32 v69, v72, v73
	v_cvt_pk_bf16_f32 v70, v74, v75
	v_cvt_pk_bf16_f32 v71, v76, v77
	s_waitcnt vmcnt(23)
	v_mfma_f32_32x32x16_bf16 v[50:65], v[114:117], v[66:69], v[50:65]
	v_cvt_pk_bf16_f32 v72, v78, v79
	v_cvt_pk_bf16_f32 v73, v80, v81
	v_add_f32_e32 v153, v153, v155
	s_waitcnt vmcnt(22)
	v_mfma_f32_32x32x16_bf16 v[34:49], v[118:121], v[66:69], v[34:49]
	s_waitcnt vmcnt(21)
	v_mfma_f32_32x32x16_bf16 v[18:33], v[122:125], v[66:69], v[18:33]
	s_waitcnt vmcnt(20)
	v_mfma_f32_32x32x16_bf16 v[2:17], v[126:129], v[66:69], v[2:17]
	s_waitcnt vmcnt(19)
	v_mfma_f32_32x32x16_bf16 v[50:65], v[130:133], v[70:73], v[50:65]
	s_waitcnt vmcnt(18)
	v_mfma_f32_32x32x16_bf16 v[34:49], v[134:137], v[70:73], v[34:49]
	s_waitcnt vmcnt(17)
	v_mfma_f32_32x32x16_bf16 v[18:33], v[138:141], v[70:73], v[18:33]
	s_waitcnt vmcnt(16)
	v_mfma_f32_32x32x16_bf16 v[2:17], v[142:145], v[70:73], v[2:17]
	global_load_dwordx4 v[114:117], v[224:225], off
	global_load_dwordx4 v[118:121], v[224:225], off offset:1024
	global_load_dwordx4 v[122:125], v[224:225], off offset:2048
	global_load_dwordx4 v[126:129], v[224:225], off offset:3072
	global_load_dwordx4 v[130:133], v[226:227], off
	global_load_dwordx4 v[134:137], v[226:227], off offset:1024
	global_load_dwordx4 v[138:141], v[226:227], off offset:2048
	global_load_dwordx4 v[142:145], v[226:227], off offset:3072
	v_lshl_add_u64 v[224:225], v[224:225], 0, s[12:13]
	v_lshl_add_u64 v[226:227], v[226:227], 0, s[12:13]
	s_waitcnt vmcnt(23)
	v_mfma_f32_32x32x16_bf16 v[66:81], v[188:191], v[82:85], 0
	s_waitcnt vmcnt(22)
	v_mfma_f32_32x32x16_bf16 v[66:81], v[192:195], v[86:89], v[66:81]
	s_waitcnt vmcnt(21)
	v_mfma_f32_32x32x16_bf16 v[66:81], v[196:199], v[90:93], v[66:81]
	s_waitcnt vmcnt(20)
	v_mfma_f32_32x32x16_bf16 v[66:81], v[200:203], v[94:97], v[66:81]
	s_waitcnt vmcnt(19)
	v_mfma_f32_32x32x16_bf16 v[66:81], v[204:207], v[98:101], v[66:81]
	s_waitcnt vmcnt(18)
	v_mfma_f32_32x32x16_bf16 v[66:81], v[208:211], v[102:105], v[66:81]
	s_waitcnt vmcnt(17)
	v_mfma_f32_32x32x16_bf16 v[66:81], v[216:219], v[106:109], v[66:81]
	s_waitcnt vmcnt(16)
	v_mfma_f32_32x32x16_bf16 v[66:81], v[220:223], v[110:113], v[66:81]
	global_load_dwordx4 v[188:191], v[228:229], off
	global_load_dwordx4 v[192:195], v[228:229], off offset:1024
	global_load_dwordx4 v[196:199], v[228:229], off offset:2048
	global_load_dwordx4 v[200:203], v[228:229], off offset:3072
	global_load_dwordx4 v[204:207], v[230:231], off
	global_load_dwordx4 v[208:211], v[230:231], off offset:1024
	global_load_dwordx4 v[216:219], v[230:231], off offset:2048
	global_load_dwordx4 v[220:223], v[230:231], off offset:3072
	v_lshl_add_u64 v[228:229], v[228:229], 0, s[12:13]
	v_lshl_add_u64 v[230:231], v[230:231], 0, s[12:13]
	s_nop 11
	v_max3_f32 v0, v66, s56, v67
	v_max3_f32 v0, v0, v68, v69
	v_max3_f32 v0, v0, v70, v71
	v_max3_f32 v0, v0, v72, v73
	v_max3_f32 v0, v0, v74, v75
	v_max3_f32 v0, v0, v76, v77
	v_max3_f32 v0, v0, v78, v79
	v_max3_f32 v0, v0, v80, v81
	v_mov_b32_e32 v155, v0
	s_nop 1
	v_permlane32_swap_b32_e32 v0, v155
	v_max_f32_e32 v155, v155, v155
	v_max_f32_e32 v0, v0, v0
	v_max_f32_e32 v0, v0, v155
	v_add_f32_e32 v155, 0x41000000, v154
	v_cmp_gt_f32_e32 vcc, v0, v155
	s_cbranch_vccnz .Lmem_upd_1
.Lmem_cont_1:
	v_sub_f32_e32 v0, v66, v154
	v_exp_f32_e32 v0, v0
	v_sub_f32_e32 v67, v67, v154
	v_exp_f32_e32 v67, v67
	v_sub_f32_e32 v68, v68, v154
	v_exp_f32_e32 v68, v68
	v_sub_f32_e32 v69, v69, v154
	v_exp_f32_e32 v69, v69
	v_sub_f32_e32 v70, v70, v154
	v_add_f32_e32 v66, 0, v0
	v_exp_f32_e32 v70, v70
	v_sub_f32_e32 v71, v71, v154
	v_add_f32_e32 v66, v67, v66
	v_exp_f32_e32 v71, v71
	v_sub_f32_e32 v72, v72, v154
	v_add_f32_e32 v66, v68, v66
	v_exp_f32_e32 v72, v72
	v_sub_f32_e32 v73, v73, v154
	v_add_f32_e32 v66, v69, v66
	v_exp_f32_e32 v73, v73
	v_sub_f32_e32 v74, v74, v154
	v_add_f32_e32 v66, v70, v66
	v_exp_f32_e32 v74, v74
	v_sub_f32_e32 v75, v75, v154
	v_add_f32_e32 v66, v71, v66
	v_exp_f32_e32 v75, v75
	v_sub_f32_e32 v76, v76, v154
	v_add_f32_e32 v66, v72, v66
	v_exp_f32_e32 v76, v76
	v_sub_f32_e32 v77, v77, v154
	v_add_f32_e32 v66, v73, v66
	v_exp_f32_e32 v77, v77
	v_sub_f32_e32 v78, v78, v154
	v_add_f32_e32 v66, v74, v66
	v_exp_f32_e32 v78, v78
	v_sub_f32_e32 v79, v79, v154
	v_add_f32_e32 v66, v75, v66
	v_exp_f32_e32 v79, v79
	v_sub_f32_e32 v80, v80, v154
	v_add_f32_e32 v66, v76, v66
	v_exp_f32_e32 v80, v80
	v_sub_f32_e32 v81, v81, v154
	v_add_f32_e32 v66, v77, v66
	v_exp_f32_e32 v81, v81
	v_add_f32_e32 v66, v78, v66
	v_add_f32_e32 v66, v79, v66
	v_add_f32_e32 v66, v80, v66
	v_add_f32_e32 v155, v81, v66
	v_cvt_pk_bf16_f32 v66, v0, v67
	v_cvt_pk_bf16_f32 v67, v68, v69
	v_cvt_pk_bf16_f32 v68, v70, v71
	v_cvt_pk_bf16_f32 v69, v72, v73
	v_cvt_pk_bf16_f32 v70, v74, v75
	v_cvt_pk_bf16_f32 v71, v76, v77
	s_waitcnt vmcnt(23)
	v_mfma_f32_32x32x16_bf16 v[50:65], v[184:187], v[66:69], v[50:65]
	v_cvt_pk_bf16_f32 v72, v78, v79
	v_cvt_pk_bf16_f32 v73, v80, v81
	v_add_f32_e32 v153, v153, v155
	s_waitcnt vmcnt(22)
	v_mfma_f32_32x32x16_bf16 v[34:49], v[156:159], v[66:69], v[34:49]
	s_waitcnt vmcnt(21)
	v_mfma_f32_32x32x16_bf16 v[18:33], v[160:163], v[66:69], v[18:33]
	s_waitcnt vmcnt(20)
	v_mfma_f32_32x32x16_bf16 v[2:17], v[164:167], v[66:69], v[2:17]
	s_waitcnt vmcnt(19)
	v_mfma_f32_32x32x16_bf16 v[50:65], v[168:171], v[70:73], v[50:65]
	s_waitcnt vmcnt(18)
	v_mfma_f32_32x32x16_bf16 v[34:49], v[172:175], v[70:73], v[34:49]
	s_waitcnt vmcnt(17)
	v_mfma_f32_32x32x16_bf16 v[18:33], v[176:179], v[70:73], v[18:33]
	s_waitcnt vmcnt(16)
	v_mfma_f32_32x32x16_bf16 v[2:17], v[180:183], v[70:73], v[2:17]
	global_load_dwordx4 v[184:187], v[224:225], off
	global_load_dwordx4 v[156:159], v[224:225], off offset:1024
	global_load_dwordx4 v[160:163], v[224:225], off offset:2048
	global_load_dwordx4 v[164:167], v[224:225], off offset:3072
	global_load_dwordx4 v[168:171], v[226:227], off
	global_load_dwordx4 v[172:175], v[226:227], off offset:1024
	global_load_dwordx4 v[176:179], v[226:227], off offset:2048
	global_load_dwordx4 v[180:183], v[226:227], off offset:3072
	v_lshl_add_u64 v[224:225], v[224:225], 0, s[12:13]
	v_lshl_add_u64 v[226:227], v[226:227], 0, s[12:13]
	s_waitcnt vmcnt(23)
	v_mfma_f32_32x32x16_bf16 v[66:81], v[114:117], v[82:85], 0
	s_waitcnt vmcnt(22)
	v_mfma_f32_32x32x16_bf16 v[66:81], v[118:121], v[86:89], v[66:81]
	s_waitcnt vmcnt(21)
	v_mfma_f32_32x32x16_bf16 v[66:81], v[122:125], v[90:93], v[66:81]
	s_waitcnt vmcnt(20)
	v_mfma_f32_32x32x16_bf16 v[66:81], v[126:129], v[94:97], v[66:81]
	s_waitcnt vmcnt(19)
	v_mfma_f32_32x32x16_bf16 v[66:81], v[130:133], v[98:101], v[66:81]
	s_waitcnt vmcnt(18)
	v_mfma_f32_32x32x16_bf16 v[66:81], v[134:137], v[102:105], v[66:81]
	s_waitcnt vmcnt(17)
	v_mfma_f32_32x32x16_bf16 v[66:81], v[138:141], v[106:109], v[66:81]
	s_waitcnt vmcnt(16)
	v_mfma_f32_32x32x16_bf16 v[66:81], v[142:145], v[110:113], v[66:81]
	global_load_dwordx4 v[114:117], v[228:229], off
	global_load_dwordx4 v[118:121], v[228:229], off offset:1024
	global_load_dwordx4 v[122:125], v[228:229], off offset:2048
	global_load_dwordx4 v[126:129], v[228:229], off offset:3072
	global_load_dwordx4 v[130:133], v[230:231], off
	global_load_dwordx4 v[134:137], v[230:231], off offset:1024
	global_load_dwordx4 v[138:141], v[230:231], off offset:2048
	global_load_dwordx4 v[142:145], v[230:231], off offset:3072
	v_lshl_add_u64 v[228:229], v[228:229], 0, s[12:13]
	v_lshl_add_u64 v[230:231], v[230:231], 0, s[12:13]
	s_nop 11
	v_max3_f32 v0, v66, s56, v67
	v_max3_f32 v0, v0, v68, v69
	v_max3_f32 v0, v0, v70, v71
	v_max3_f32 v0, v0, v72, v73
	v_max3_f32 v0, v0, v74, v75
	v_max3_f32 v0, v0, v76, v77
	v_max3_f32 v0, v0, v78, v79
	v_max3_f32 v0, v0, v80, v81
	v_mov_b32_e32 v155, v0
	s_nop 1
	v_permlane32_swap_b32_e32 v0, v155
	v_max_f32_e32 v155, v155, v155
	v_max_f32_e32 v0, v0, v0
	v_max_f32_e32 v0, v0, v155
	v_add_f32_e32 v155, 0x41000000, v154
	v_cmp_gt_f32_e32 vcc, v0, v155
	s_cbranch_vccnz .Lmem_upd_2
.Lmem_cont_2:
	v_sub_f32_e32 v0, v66, v154
	v_exp_f32_e32 v0, v0
	v_sub_f32_e32 v67, v67, v154
	v_exp_f32_e32 v67, v67
	v_sub_f32_e32 v68, v68, v154
	v_exp_f32_e32 v68, v68
	v_sub_f32_e32 v69, v69, v154
	v_exp_f32_e32 v69, v69
	v_sub_f32_e32 v70, v70, v154
	v_add_f32_e32 v66, 0, v0
	v_exp_f32_e32 v70, v70
	v_sub_f32_e32 v71, v71, v154
	v_add_f32_e32 v66, v67, v66
	v_exp_f32_e32 v71, v71
	v_sub_f32_e32 v72, v72, v154
	v_add_f32_e32 v66, v68, v66
	v_exp_f32_e32 v72, v72
	v_sub_f32_e32 v73, v73, v154
	v_add_f32_e32 v66, v69, v66
	v_exp_f32_e32 v73, v73
	v_sub_f32_e32 v74, v74, v154
	v_add_f32_e32 v66, v70, v66
	v_exp_f32_e32 v74, v74
	v_sub_f32_e32 v75, v75, v154
	v_add_f32_e32 v66, v71, v66
	v_exp_f32_e32 v75, v75
	v_sub_f32_e32 v76, v76, v154
	v_add_f32_e32 v66, v72, v66
	v_exp_f32_e32 v76, v76
	v_sub_f32_e32 v77, v77, v154
	v_add_f32_e32 v66, v73, v66
	v_exp_f32_e32 v77, v77
	v_sub_f32_e32 v78, v78, v154
	v_add_f32_e32 v66, v74, v66
	v_exp_f32_e32 v78, v78
	v_sub_f32_e32 v79, v79, v154
	v_add_f32_e32 v66, v75, v66
	v_exp_f32_e32 v79, v79
	v_sub_f32_e32 v80, v80, v154
	v_add_f32_e32 v66, v76, v66
	v_exp_f32_e32 v80, v80
	v_sub_f32_e32 v81, v81, v154
	v_add_f32_e32 v66, v77, v66
	v_exp_f32_e32 v81, v81
	v_add_f32_e32 v66, v78, v66
	v_add_f32_e32 v66, v79, v66
	v_add_f32_e32 v66, v80, v66
	v_add_f32_e32 v155, v81, v66
	v_cvt_pk_bf16_f32 v66, v0, v67
	v_cvt_pk_bf16_f32 v67, v68, v69
	v_cvt_pk_bf16_f32 v68, v70, v71
	v_cvt_pk_bf16_f32 v69, v72, v73
	v_cvt_pk_bf16_f32 v70, v74, v75
	v_cvt_pk_bf16_f32 v71, v76, v77
	s_waitcnt vmcnt(23)
	v_mfma_f32_32x32x16_bf16 v[50:65], v[188:191], v[66:69], v[50:65]
	v_cvt_pk_bf16_f32 v72, v78, v79
	v_cvt_pk_bf16_f32 v73, v80, v81
	v_add_f32_e32 v153, v153, v155
	s_waitcnt vmcnt(22)
	v_mfma_f32_32x32x16_bf16 v[34:49], v[192:195], v[66:69], v[34:49]
	s_waitcnt vmcnt(21)
	v_mfma_f32_32x32x16_bf16 v[18:33], v[196:199], v[66:69], v[18:33]
	s_waitcnt vmcnt(20)
	v_mfma_f32_32x32x16_bf16 v[2:17], v[200:203], v[66:69], v[2:17]
	s_waitcnt vmcnt(19)
	v_mfma_f32_32x32x16_bf16 v[50:65], v[204:207], v[70:73], v[50:65]
	s_waitcnt vmcnt(18)
	v_mfma_f32_32x32x16_bf16 v[34:49], v[208:211], v[70:73], v[34:49]
	s_waitcnt vmcnt(17)
	v_mfma_f32_32x32x16_bf16 v[18:33], v[216:219], v[70:73], v[18:33]
	s_waitcnt vmcnt(16)
	v_mfma_f32_32x32x16_bf16 v[2:17], v[220:223], v[70:73], v[2:17]
	global_load_dwordx4 v[188:191], v[224:225], off
	global_load_dwordx4 v[192:195], v[224:225], off offset:1024
	global_load_dwordx4 v[196:199], v[224:225], off offset:2048
	global_load_dwordx4 v[200:203], v[224:225], off offset:3072
	global_load_dwordx4 v[204:207], v[226:227], off
	global_load_dwordx4 v[208:211], v[226:227], off offset:1024
	global_load_dwordx4 v[216:219], v[226:227], off offset:2048
	global_load_dwordx4 v[220:223], v[226:227], off offset:3072
	v_lshl_add_u64 v[224:225], v[224:225], 0, s[12:13]
	v_lshl_add_u64 v[226:227], v[226:227], 0, s[12:13]
	s_waitcnt vmcnt(23)
	v_mfma_f32_32x32x16_bf16 v[66:81], v[184:187], v[82:85], 0
	s_waitcnt vmcnt(22)
	v_mfma_f32_32x32x16_bf16 v[66:81], v[156:159], v[86:89], v[66:81]
	s_waitcnt vmcnt(21)
	v_mfma_f32_32x32x16_bf16 v[66:81], v[160:163], v[90:93], v[66:81]
	s_waitcnt vmcnt(20)
	v_mfma_f32_32x32x16_bf16 v[66:81], v[164:167], v[94:97], v[66:81]
	s_waitcnt vmcnt(19)
	v_mfma_f32_32x32x16_bf16 v[66:81], v[168:171], v[98:101], v[66:81]
	s_waitcnt vmcnt(18)
	v_mfma_f32_32x32x16_bf16 v[66:81], v[172:175], v[102:105], v[66:81]
	s_waitcnt vmcnt(17)
	v_mfma_f32_32x32x16_bf16 v[66:81], v[176:179], v[106:109], v[66:81]
	s_waitcnt vmcnt(16)
	v_mfma_f32_32x32x16_bf16 v[66:81], v[180:183], v[110:113], v[66:81]
	global_load_dwordx4 v[184:187], v[228:229], off
	global_load_dwordx4 v[156:159], v[228:229], off offset:1024
	global_load_dwordx4 v[160:163], v[228:229], off offset:2048
	global_load_dwordx4 v[164:167], v[228:229], off offset:3072
	global_load_dwordx4 v[168:171], v[230:231], off
	global_load_dwordx4 v[172:175], v[230:231], off offset:1024
	global_load_dwordx4 v[176:179], v[230:231], off offset:2048
	global_load_dwordx4 v[180:183], v[230:231], off offset:3072
	v_lshl_add_u64 v[228:229], v[228:229], 0, s[12:13]
	v_lshl_add_u64 v[230:231], v[230:231], 0, s[12:13]
	s_nop 11
	v_max3_f32 v0, v66, s56, v67
	v_max3_f32 v0, v0, v68, v69
	v_max3_f32 v0, v0, v70, v71
	v_max3_f32 v0, v0, v72, v73
	v_max3_f32 v0, v0, v74, v75
	v_max3_f32 v0, v0, v76, v77
	v_max3_f32 v0, v0, v78, v79
	v_max3_f32 v0, v0, v80, v81
	v_mov_b32_e32 v155, v0
	s_nop 1
	v_permlane32_swap_b32_e32 v0, v155
	v_max_f32_e32 v155, v155, v155
	v_max_f32_e32 v0, v0, v0
	v_max_f32_e32 v0, v0, v155
	v_add_f32_e32 v155, 0x41000000, v154
	v_cmp_gt_f32_e32 vcc, v0, v155
	s_cbranch_vccnz .Lmem_upd_3

.Lmem_cont_6:
	v_sub_f32_e32 v0, v66, v154
	v_exp_f32_e32 v0, v0
	v_sub_f32_e32 v67, v67, v154
	v_exp_f32_e32 v67, v67
	v_sub_f32_e32 v68, v68, v154
	v_exp_f32_e32 v68, v68
	v_sub_f32_e32 v69, v69, v154
	v_exp_f32_e32 v69, v69
	v_sub_f32_e32 v70, v70, v154
	v_add_f32_e32 v66, 0, v0
	v_exp_f32_e32 v70, v70
	v_sub_f32_e32 v71, v71, v154
	v_add_f32_e32 v66, v67, v66
	v_exp_f32_e32 v71, v71
	v_sub_f32_e32 v72, v72, v154
	v_add_f32_e32 v66, v68, v66
	v_exp_f32_e32 v72, v72
	v_sub_f32_e32 v73, v73, v154
	v_add_f32_e32 v66, v69, v66
	v_exp_f32_e32 v73, v73
	v_sub_f32_e32 v74, v74, v154
	v_add_f32_e32 v66, v70, v66
	v_exp_f32_e32 v74, v74
	v_sub_f32_e32 v75, v75, v154
	v_add_f32_e32 v66, v71, v66
	v_exp_f32_e32 v75, v75
	v_sub_f32_e32 v76, v76, v154
	v_add_f32_e32 v66, v72, v66
	v_exp_f32_e32 v76, v76
	v_sub_f32_e32 v77, v77, v154
	v_add_f32_e32 v66, v73, v66
	v_exp_f32_e32 v77, v77
	v_sub_f32_e32 v78, v78, v154
	v_add_f32_e32 v66, v74, v66
	v_exp_f32_e32 v78, v78
	v_sub_f32_e32 v79, v79, v154
	v_add_f32_e32 v66, v75, v66
	v_exp_f32_e32 v79, v79
	v_sub_f32_e32 v80, v80, v154
	v_add_f32_e32 v66, v76, v66
	v_exp_f32_e32 v80, v80
	v_sub_f32_e32 v81, v81, v154
	v_add_f32_e32 v66, v77, v66
	v_exp_f32_e32 v81, v81
	v_add_f32_e32 v66, v78, v66
	v_add_f32_e32 v66, v79, v66
	v_add_f32_e32 v66, v80, v66
	v_add_f32_e32 v155, v81, v66
	v_cvt_pk_bf16_f32 v66, v0, v67
	v_cvt_pk_bf16_f32 v67, v68, v69
	v_cvt_pk_bf16_f32 v68, v70, v71
	v_cvt_pk_bf16_f32 v69, v72, v73
	v_cvt_pk_bf16_f32 v70, v74, v75
	v_cvt_pk_bf16_f32 v71, v76, v77
	s_waitcnt vmcnt(23)
	v_mfma_f32_32x32x16_bf16 v[50:65], v[114:117], v[66:69], v[50:65]
	v_cvt_pk_bf16_f32 v72, v78, v79
	v_cvt_pk_bf16_f32 v73, v80, v81
	v_add_f32_e32 v153, v153, v155
	s_waitcnt vmcnt(22)
	v_mfma_f32_32x32x16_bf16 v[34:49], v[118:121], v[66:69], v[34:49]
	s_waitcnt vmcnt(21)
	v_mfma_f32_32x32x16_bf16 v[18:33], v[122:125], v[66:69], v[18:33]
	s_waitcnt vmcnt(20)
	v_mfma_f32_32x32x16_bf16 v[2:17], v[126:129], v[66:69], v[2:17]
	s_waitcnt vmcnt(19)
	v_mfma_f32_32x32x16_bf16 v[50:65], v[130:133], v[70:73], v[50:65]
	s_waitcnt vmcnt(18)
	v_mfma_f32_32x32x16_bf16 v[34:49], v[134:137], v[70:73], v[34:49]
	s_waitcnt vmcnt(17)
	v_mfma_f32_32x32x16_bf16 v[18:33], v[138:141], v[70:73], v[18:33]
	s_waitcnt vmcnt(16)
	v_mfma_f32_32x32x16_bf16 v[2:17], v[142:145], v[70:73], v[2:17]
	s_waitcnt vmcnt(15)
	v_mfma_f32_32x32x16_bf16 v[66:81], v[188:191], v[82:85], 0
	s_waitcnt vmcnt(14)
	v_mfma_f32_32x32x16_bf16 v[66:81], v[192:195], v[86:89], v[66:81]
	s_waitcnt vmcnt(13)
	v_mfma_f32_32x32x16_bf16 v[66:81], v[196:199], v[90:93], v[66:81]
	s_waitcnt vmcnt(12)
	v_mfma_f32_32x32x16_bf16 v[66:81], v[200:203], v[94:97], v[66:81]
	s_waitcnt vmcnt(11)
	v_mfma_f32_32x32x16_bf16 v[66:81], v[204:207], v[98:101], v[66:81]
	s_waitcnt vmcnt(10)
	v_mfma_f32_32x32x16_bf16 v[66:81], v[208:211], v[102:105], v[66:81]
	s_waitcnt vmcnt(9)
	v_mfma_f32_32x32x16_bf16 v[66:81], v[216:219], v[106:109], v[66:81]
	s_waitcnt vmcnt(8)
	v_mfma_f32_32x32x16_bf16 v[66:81], v[220:223], v[110:113], v[66:81]
	s_nop 11
	v_max3_f32 v0, v66, s56, v67
	v_max3_f32 v0, v0, v68, v69
	v_max3_f32 v0, v0, v70, v71
	v_max3_f32 v0, v0, v72, v73
	v_max3_f32 v0, v0, v74, v75
	v_max3_f32 v0, v0, v76, v77
	v_max3_f32 v0, v0, v78, v79
	v_max3_f32 v0, v0, v80, v81
	v_mov_b32_e32 v155, v0
	s_nop 1
	v_permlane32_swap_b32_e32 v0, v155
	v_max_f32_e32 v155, v155, v155
	v_max_f32_e32 v0, v0, v0
	v_max_f32_e32 v0, v0, v155
	v_add_f32_e32 v155, 0x41000000, v154
	v_cmp_gt_f32_e32 vcc, v0, v155
	s_cbranch_vccnz .Lmem_upd_7
.Lmem_cont_7:
	v_sub_f32_e32 v0, v66, v154
	v_exp_f32_e32 v0, v0
	v_sub_f32_e32 v67, v67, v154
	v_exp_f32_e32 v67, v67
	v_sub_f32_e32 v68, v68, v154
	v_exp_f32_e32 v68, v68
	v_sub_f32_e32 v69, v69, v154
	v_exp_f32_e32 v69, v69
	v_sub_f32_e32 v70, v70, v154
	v_add_f32_e32 v66, 0, v0
	v_exp_f32_e32 v70, v70
	v_sub_f32_e32 v71, v71, v154
	v_add_f32_e32 v66, v67, v66
	v_exp_f32_e32 v71, v71
	v_sub_f32_e32 v72, v72, v154
	v_add_f32_e32 v66, v68, v66
	v_exp_f32_e32 v72, v72
	v_sub_f32_e32 v73, v73, v154
	v_add_f32_e32 v66, v69, v66
	v_exp_f32_e32 v73, v73
	v_sub_f32_e32 v74, v74, v154
	v_add_f32_e32 v66, v70, v66
	v_exp_f32_e32 v74, v74
	v_sub_f32_e32 v75, v75, v154
	v_add_f32_e32 v66, v71, v66
	v_exp_f32_e32 v75, v75
	v_sub_f32_e32 v76, v76, v154
	v_add_f32_e32 v66, v72, v66
	v_exp_f32_e32 v76, v76
	v_sub_f32_e32 v77, v77, v154
	v_add_f32_e32 v66, v73, v66
	v_exp_f32_e32 v77, v77
	v_sub_f32_e32 v78, v78, v154
	v_add_f32_e32 v66, v74, v66
	v_exp_f32_e32 v78, v78
	v_sub_f32_e32 v79, v79, v154
	v_add_f32_e32 v66, v75, v66
	v_exp_f32_e32 v79, v79
	v_sub_f32_e32 v80, v80, v154
	v_add_f32_e32 v66, v76, v66
	v_exp_f32_e32 v80, v80
	v_sub_f32_e32 v81, v81, v154
	v_add_f32_e32 v66, v77, v66
	v_exp_f32_e32 v81, v81
	v_add_f32_e32 v66, v78, v66
	v_add_f32_e32 v66, v79, v66
	v_add_f32_e32 v66, v80, v66
	v_add_f32_e32 v155, v81, v66
	v_cvt_pk_bf16_f32 v66, v0, v67
	v_cvt_pk_bf16_f32 v67, v68, v69
	v_cvt_pk_bf16_f32 v68, v70, v71
	v_cvt_pk_bf16_f32 v69, v72, v73
	v_cvt_pk_bf16_f32 v70, v74, v75
	v_cvt_pk_bf16_f32 v71, v76, v77
	s_waitcnt vmcnt(7)
	v_mfma_f32_32x32x16_bf16 v[50:65], v[184:187], v[66:69], v[50:65]
	v_cvt_pk_bf16_f32 v72, v78, v79
	v_cvt_pk_bf16_f32 v73, v80, v81
	v_add_f32_e32 v153, v153, v155
	s_waitcnt vmcnt(6)
	v_mfma_f32_32x32x16_bf16 v[34:49], v[156:159], v[66:69], v[34:49]
	s_waitcnt vmcnt(5)
	v_mfma_f32_32x32x16_bf16 v[18:33], v[160:163], v[66:69], v[18:33]
	s_waitcnt vmcnt(4)
	v_mfma_f32_32x32x16_bf16 v[2:17], v[164:167], v[66:69], v[2:17]
	s_waitcnt vmcnt(3)
	v_mfma_f32_32x32x16_bf16 v[50:65], v[168:171], v[70:73], v[50:65]
	s_waitcnt vmcnt(2)
	v_mfma_f32_32x32x16_bf16 v[34:49], v[172:175], v[70:73], v[34:49]
	s_waitcnt vmcnt(1)
	v_mfma_f32_32x32x16_bf16 v[18:33], v[176:179], v[70:73], v[18:33]
	s_waitcnt vmcnt(0)
	v_mfma_f32_32x32x16_bf16 v[2:17], v[180:183], v[70:73], v[2:17]
	s_branch .LBB0_664
.Lmem_upd_0:
	s_nop 0
	v_cndmask_b32_e32 v155, v154, v0, vcc
	v_sub_f32_e32 v0, v154, v155
	v_exp_f32_e32 v0, v0
	v_mov_b32_e32 v154, v155
	v_mul_f32_e32 v153, v153, v0
	v_pk_mul_f32 v[64:65], v[64:65], v[0:1] op_sel_hi:[1,0]
	v_pk_mul_f32 v[62:63], v[62:63], v[0:1] op_sel_hi:[1,0]
	v_pk_mul_f32 v[60:61], v[60:61], v[0:1] op_sel_hi:[1,0]
	v_pk_mul_f32 v[58:59], v[58:59], v[0:1] op_sel_hi:[1,0]
	v_pk_mul_f32 v[56:57], v[56:57], v[0:1] op_sel_hi:[1,0]
	v_pk_mul_f32 v[54:55], v[54:55], v[0:1] op_sel_hi:[1,0]
	v_pk_mul_f32 v[52:53], v[52:53], v[0:1] op_sel_hi:[1,0]
	v_pk_mul_f32 v[50:51], v[50:51], v[0:1] op_sel_hi:[1,0]
	v_pk_mul_f32 v[48:49], v[48:49], v[0:1] op_sel_hi:[1,0]
	v_pk_mul_f32 v[46:47], v[46:47], v[0:1] op_sel_hi:[1,0]
	v_pk_mul_f32 v[44:45], v[44:45], v[0:1] op_sel_hi:[1,0]
	v_pk_mul_f32 v[42:43], v[42:43], v[0:1] op_sel_hi:[1,0]
	v_pk_mul_f32 v[40:41], v[40:41], v[0:1] op_sel_hi:[1,0]
	v_pk_mul_f32 v[38:39], v[38:39], v[0:1] op_sel_hi:[1,0]
	v_pk_mul_f32 v[36:37], v[36:37], v[0:1] op_sel_hi:[1,0]
	v_pk_mul_f32 v[34:35], v[34:35], v[0:1] op_sel_hi:[1,0]
	v_pk_mul_f32 v[32:33], v[32:33], v[0:1] op_sel_hi:[1,0]
	v_pk_mul_f32 v[30:31], v[30:31], v[0:1] op_sel_hi:[1,0]
	v_pk_mul_f32 v[28:29], v[28:29], v[0:1] op_sel_hi:[1,0]
	v_pk_mul_f32 v[26:27], v[26:27], v[0:1] op_sel_hi:[1,0]
	v_pk_mul_f32 v[24:25], v[24:25], v[0:1] op_sel_hi:[1,0]
	v_pk_mul_f32 v[22:23], v[22:23], v[0:1] op_sel_hi:[1,0]
	v_pk_mul_f32 v[20:21], v[20:21], v[0:1] op_sel_hi:[1,0]
	v_pk_mul_f32 v[18:19], v[18:19], v[0:1] op_sel_hi:[1,0]
	v_pk_mul_f32 v[16:17], v[16:17], v[0:1] op_sel_hi:[1,0]
	v_pk_mul_f32 v[14:15], v[14:15], v[0:1] op_sel_hi:[1,0]
	v_pk_mul_f32 v[12:13], v[12:13], v[0:1] op_sel_hi:[1,0]
	v_pk_mul_f32 v[10:11], v[10:11], v[0:1] op_sel_hi:[1,0]
	v_pk_mul_f32 v[8:9], v[8:9], v[0:1] op_sel_hi:[1,0]
	v_pk_mul_f32 v[6:7], v[6:7], v[0:1] op_sel_hi:[1,0]
	v_pk_mul_f32 v[4:5], v[4:5], v[0:1] op_sel_hi:[1,0]
	v_pk_mul_f32 v[2:3], v[2:3], v[0:1] op_sel_hi:[1,0]
	s_branch .Lmem_cont_0
